# mixer-A unit boundary: batched O readback, no store drain before next unit DMA, acc zeroing before DMA wait
# baseline (speedup 1.0000x reference)
.LBB0_405:
	s_or_b64 exec, exec, s[4:5]
	s_waitcnt lgkmcnt(0)
	v_lshlrev_b32_e32 v129, 2, v134
	global_load_dword v132, v129, s[0:1]
	global_load_dword v131, v129, s[0:1] offset:128
	global_load_dword v130, v129, s[0:1] offset:256
	s_nop 0
	global_load_dword v129, v129, s[0:1] offset:384
	v_ashrrev_i32_e32 v135, 3, v128
	v_and_b32_e32 v139, -4, v135
	v_mov_b32_e32 v133, v200
	v_lshl_add_u32 v143, v134, 1, s48
	v_lshl_add_u32 v134, v139, 2, s59
	ds_read_b96 v[136:138], v134
	ds_read_b96 v[140:142], v134 offset:128
	v_sub_f32_e32 v133, 1.0, v133
	s_add_i32 s6, s6, 1
	s_cmp_eq_u32 s6, 4
	s_waitcnt lgkmcnt(0)
	v_mul_f32_e32 v16, v16, v140
	v_mul_f32_e32 v0, v0, v140
	v_fma_f32 v16, v80, v136, -v16
	v_fma_f32 v0, v64, v136, -v0
	v_mul_f32_e32 v64, v16, v16
	v_mul_f32_e32 v32, v32, v140
	v_fmac_f32_e32 v64, v0, v0
	v_fma_f32 v80, v96, v136, -v32
	v_mul_f32_e32 v32, v48, v140
	v_fmac_f32_e32 v64, v80, v80
	v_fma_f32 v48, v112, v136, -v32
	v_fmac_f32_e32 v64, v48, v48
	s_nop 1
	v_add_f32_dpp v32, v64, v64 quad_perm:[1,0,3,2] row_mask:0xf bank_mask:0xf
	s_nop 1
	v_add_f32_dpp v32, v32, v32 quad_perm:[2,3,0,1] row_mask:0xf bank_mask:0xf
	s_nop 1
	v_add_f32_dpp v32, v32, v32 row_half_mirror row_mask:0xf bank_mask:0xf
	s_nop 1
	v_add_f32_dpp v32, v32, v32 row_mirror row_mask:0xf bank_mask:0xf
	v_mov_b32_e32 v64, v32
	s_nop 1
	v_permlane16_swap_b32_e32 v32, v64
	v_add_f32_e32 v32, v32, v64
	v_fmamk_f32 v32, v32, 0x3c000000, v204
	v_rsq_f32_e32 v32, v32
	s_nop 0
	v_mul_f32_e32 v64, v133, v32
	v_mul_f32_e32 v0, v0, v64
	v_mul_f32_e32 v16, v16, v64
	v_lshl_add_u32 v32, v139, 8, v143
	v_mul_f32_e32 v80, v80, v64
	v_mul_f32_e32 v48, v48, v64
	s_waitcnt vmcnt(3)
	v_mul_f32_e32 v0, v132, v0
	s_waitcnt vmcnt(2)
	v_mul_f32_e32 v16, v131, v16
	v_cvt_pk_bf16_f32 v0, v0, s0
	s_waitcnt vmcnt(1)
	v_mul_f32_e32 v80, v130, v80
	ds_write_b16 v32, v0
	v_cvt_pk_bf16_f32 v0, v16, s0
	s_waitcnt vmcnt(0)
	v_mul_f32_e32 v48, v129, v48
	ds_write_b16 v32, v0 offset:64
	v_cvt_pk_bf16_f32 v0, v80, s0
	ds_write_b16 v32, v0 offset:128
	v_cvt_pk_bf16_f32 v0, v48, s0
	ds_write_b16 v32, v0 offset:192
	v_mul_f32_e32 v0, v1, v141
	v_mul_f32_e32 v1, v17, v141
	v_fma_f32 v1, v81, v137, -v1
	v_fma_f32 v0, v65, v137, -v0
	v_mul_f32_e32 v16, v1, v1
	v_mul_f32_e32 v17, v33, v141
	v_fmac_f32_e32 v16, v0, v0
	v_fma_f32 v17, v97, v137, -v17
	v_mul_f32_e32 v33, v49, v141
	v_fmac_f32_e32 v16, v17, v17
	v_fma_f32 v33, v113, v137, -v33
	v_fmac_f32_e32 v16, v33, v33
	s_nop 1
	v_add_f32_dpp v16, v16, v16 quad_perm:[1,0,3,2] row_mask:0xf bank_mask:0xf
	s_nop 1
	v_add_f32_dpp v16, v16, v16 quad_perm:[2,3,0,1] row_mask:0xf bank_mask:0xf
	s_nop 1
	v_add_f32_dpp v16, v16, v16 row_half_mirror row_mask:0xf bank_mask:0xf
	s_nop 1
	v_add_f32_dpp v16, v16, v16 row_mirror row_mask:0xf bank_mask:0xf
	v_mov_b32_e32 v48, v16
	s_nop 1
	v_permlane16_swap_b32_e32 v16, v48
	v_add_f32_e32 v16, v16, v48
	v_fmamk_f32 v16, v16, 0x3c000000, v204
	v_rsq_f32_e32 v16, v16
	s_nop 0
	v_mul_f32_e32 v16, v133, v16
	v_mul_f32_e32 v0, v0, v16
	v_mul_f32_e32 v0, v132, v0
	v_mul_f32_e32 v1, v1, v16
	v_mul_f32_e32 v1, v131, v1
	v_mul_f32_e32 v17, v17, v16
	v_cvt_pk_bf16_f32 v0, v0, s0
	v_mul_f32_e32 v17, v130, v17
	v_mul_f32_e32 v16, v33, v16
	ds_write_b16 v32, v0 offset:256
	v_cvt_pk_bf16_f32 v0, v1, s0
	v_mul_f32_e32 v16, v129, v16
	ds_write_b16 v32, v0 offset:320
	v_cvt_pk_bf16_f32 v0, v17, s0
	ds_write_b16 v32, v0 offset:384
	v_cvt_pk_bf16_f32 v0, v16, s0
	v_mul_f32_e32 v1, v18, v142
	ds_write_b16 v32, v0 offset:448
	v_mul_f32_e32 v0, v2, v142
	v_fma_f32 v1, v82, v138, -v1
	v_fma_f32 v0, v66, v138, -v0
	v_mul_f32_e32 v2, v1, v1
	v_mul_f32_e32 v16, v34, v142
	v_fmac_f32_e32 v2, v0, v0
	v_fma_f32 v16, v98, v138, -v16
	v_mul_f32_e32 v17, v50, v142
	v_fmac_f32_e32 v2, v16, v16
	v_fma_f32 v17, v114, v138, -v17
	v_fmac_f32_e32 v2, v17, v17
	s_nop 1
	v_add_f32_dpp v2, v2, v2 quad_perm:[1,0,3,2] row_mask:0xf bank_mask:0xf
	s_nop 1
	v_add_f32_dpp v2, v2, v2 quad_perm:[2,3,0,1] row_mask:0xf bank_mask:0xf
	s_nop 1
	v_add_f32_dpp v2, v2, v2 row_half_mirror row_mask:0xf bank_mask:0xf
	s_nop 1
	v_add_f32_dpp v2, v2, v2 row_mirror row_mask:0xf bank_mask:0xf
	v_mov_b32_e32 v18, v2
	s_nop 1
	v_permlane16_swap_b32_e32 v2, v18
	v_add_f32_e32 v2, v2, v18
	v_fmamk_f32 v2, v2, 0x3c000000, v204
	v_rsq_f32_e32 v2, v2
	s_nop 0
	v_mul_f32_e32 v2, v133, v2
	v_mul_f32_e32 v0, v0, v2
	v_mul_f32_e32 v0, v132, v0
	v_mul_f32_e32 v1, v1, v2
	v_mul_f32_e32 v1, v131, v1
	v_mul_f32_e32 v16, v16, v2
	v_cvt_pk_bf16_f32 v0, v0, s0
	v_mul_f32_e32 v16, v130, v16
	v_mul_f32_e32 v2, v17, v2
	ds_write_b16 v32, v0 offset:512
	v_cvt_pk_bf16_f32 v0, v1, s0
	v_mul_f32_e32 v2, v129, v2
	ds_write_b16 v32, v0 offset:576
	v_cvt_pk_bf16_f32 v0, v16, s0
	ds_write_b16 v32, v0 offset:640
	v_cvt_pk_bf16_f32 v0, v2, s0
	v_or_b32_e32 v2, 3, v135
	ds_write_b16 v32, v0 offset:704
	v_lshl_add_u32 v0, v2, 2, s59
	ds_read2_b32 v[0:1], v0 offset1:32
	v_lshl_add_u32 v2, v2, 8, v143
	s_waitcnt lgkmcnt(0)
	v_mul_f32_e32 v16, v19, v1
	v_mul_f32_e32 v3, v3, v1
	v_fma_f32 v16, v83, v0, -v16
	v_fma_f32 v3, v67, v0, -v3
	v_mul_f32_e32 v17, v16, v16
	v_mul_f32_e32 v18, v35, v1
	v_fmac_f32_e32 v17, v3, v3
	v_fma_f32 v18, v99, v0, -v18
	v_mul_f32_e32 v1, v51, v1
	v_fmac_f32_e32 v17, v18, v18
	v_fma_f32 v0, v115, v0, -v1
	v_fmac_f32_e32 v17, v0, v0
	s_nop 1
	v_add_f32_dpp v1, v17, v17 quad_perm:[1,0,3,2] row_mask:0xf bank_mask:0xf
	s_nop 1
	v_add_f32_dpp v1, v1, v1 quad_perm:[2,3,0,1] row_mask:0xf bank_mask:0xf
	s_nop 1
	v_add_f32_dpp v1, v1, v1 row_half_mirror row_mask:0xf bank_mask:0xf
	s_nop 1
	v_add_f32_dpp v1, v1, v1 row_mirror row_mask:0xf bank_mask:0xf
	v_mov_b32_e32 v17, v1
	s_nop 1
	v_permlane16_swap_b32_e32 v1, v17
	v_add_f32_e32 v1, v1, v17
	v_fmamk_f32 v1, v1, 0x3c000000, v204
	v_rsq_f32_e32 v1, v1
	s_nop 0
	v_mul_f32_e32 v1, v133, v1
	v_mul_f32_e32 v3, v3, v1
	v_mul_f32_e32 v3, v132, v3
	v_mul_f32_e32 v16, v16, v1
	v_mul_f32_e32 v16, v131, v16
	v_mul_f32_e32 v17, v18, v1
	v_mul_f32_e32 v0, v0, v1
	v_cvt_pk_bf16_f32 v1, v3, s0
	v_mul_f32_e32 v17, v130, v17
	v_mul_f32_e32 v0, v129, v0
	ds_write_b16 v2, v1
	v_cvt_pk_bf16_f32 v1, v16, s0
	ds_write_b16 v2, v1 offset:64
	v_cvt_pk_bf16_f32 v1, v17, s0
	v_cvt_pk_bf16_f32 v0, v0, s0
	ds_write_b16 v2, v1 offset:128
	ds_write_b16 v2, v0 offset:192
	ds_read_b128 v[0:3], v134 offset:32
	ds_read_b128 v[16:19], v134 offset:160
	s_waitcnt lgkmcnt(0)
	v_mul_f32_e32 v20, v20, v16
	v_mul_f32_e32 v4, v4, v16
	v_fma_f32 v20, v84, v0, -v20
	v_fma_f32 v4, v68, v0, -v4
	v_mul_f32_e32 v33, v20, v20
	v_mul_f32_e32 v34, v36, v16
	v_fmac_f32_e32 v33, v4, v4
	v_fma_f32 v34, v100, v0, -v34
	v_mul_f32_e32 v16, v52, v16
	v_fmac_f32_e32 v33, v34, v34
	v_fma_f32 v0, v116, v0, -v16
	v_fmac_f32_e32 v33, v0, v0
	s_nop 1
	v_add_f32_dpp v16, v33, v33 quad_perm:[1,0,3,2] row_mask:0xf bank_mask:0xf
	s_nop 1
	v_add_f32_dpp v16, v16, v16 quad_perm:[2,3,0,1] row_mask:0xf bank_mask:0xf
	s_nop 1
	v_add_f32_dpp v16, v16, v16 row_half_mirror row_mask:0xf bank_mask:0xf
	s_nop 1
	v_add_f32_dpp v16, v16, v16 row_mirror row_mask:0xf bank_mask:0xf
	v_mov_b32_e32 v33, v16
	s_nop 1
	v_permlane16_swap_b32_e32 v16, v33
	v_add_f32_e32 v16, v16, v33
	v_fmamk_f32 v16, v16, 0x3c000000, v204
	v_rsq_f32_e32 v16, v16
	s_nop 0
	v_mul_f32_e32 v16, v133, v16
	v_mul_f32_e32 v4, v4, v16
	v_mul_f32_e32 v4, v132, v4
	v_mul_f32_e32 v20, v20, v16
	v_mul_f32_e32 v20, v131, v20
	v_mul_f32_e32 v33, v34, v16
	v_cvt_pk_bf16_f32 v4, v4, s0
	v_mul_f32_e32 v33, v130, v33
	v_mul_f32_e32 v0, v0, v16
	ds_write_b16 v32, v4 offset:2048
	v_cvt_pk_bf16_f32 v4, v20, s0
	v_mul_f32_e32 v0, v129, v0
	ds_write_b16 v32, v4 offset:2112
	v_cvt_pk_bf16_f32 v4, v33, s0
	ds_write_b16 v32, v4 offset:2176
	v_cvt_pk_bf16_f32 v0, v0, s0
	v_mul_f32_e32 v4, v21, v17
	ds_write_b16 v32, v0 offset:2240
	v_mul_f32_e32 v0, v5, v17
	v_fma_f32 v4, v85, v1, -v4
	v_fma_f32 v0, v69, v1, -v0
	v_mul_f32_e32 v5, v4, v4
	v_mul_f32_e32 v16, v37, v17
	v_fmac_f32_e32 v5, v0, v0
	v_fma_f32 v16, v101, v1, -v16
	v_mul_f32_e32 v17, v53, v17
	v_fmac_f32_e32 v5, v16, v16
	v_fma_f32 v1, v117, v1, -v17
	v_fmac_f32_e32 v5, v1, v1
	s_nop 1
	v_add_f32_dpp v5, v5, v5 quad_perm:[1,0,3,2] row_mask:0xf bank_mask:0xf
	s_nop 1
	v_add_f32_dpp v5, v5, v5 quad_perm:[2,3,0,1] row_mask:0xf bank_mask:0xf
	s_nop 1
	v_add_f32_dpp v5, v5, v5 row_half_mirror row_mask:0xf bank_mask:0xf
	s_nop 1
	v_add_f32_dpp v5, v5, v5 row_mirror row_mask:0xf bank_mask:0xf
	v_mov_b32_e32 v17, v5
	s_nop 1
	v_permlane16_swap_b32_e32 v5, v17
	v_add_f32_e32 v5, v5, v17
	v_fmamk_f32 v5, v5, 0x3c000000, v204
	v_rsq_f32_e32 v5, v5
	s_nop 0
	v_mul_f32_e32 v5, v133, v5
	v_mul_f32_e32 v0, v0, v5
	v_mul_f32_e32 v0, v132, v0
	v_mul_f32_e32 v4, v4, v5
	v_mul_f32_e32 v4, v131, v4
	v_mul_f32_e32 v16, v16, v5
	v_cvt_pk_bf16_f32 v0, v0, s0
	v_mul_f32_e32 v16, v130, v16
	v_mul_f32_e32 v1, v1, v5
	ds_write_b16 v32, v0 offset:2304
	v_cvt_pk_bf16_f32 v0, v4, s0
	v_mul_f32_e32 v1, v129, v1
	ds_write_b16 v32, v0 offset:2368
	v_cvt_pk_bf16_f32 v0, v16, s0
	ds_write_b16 v32, v0 offset:2432
	v_cvt_pk_bf16_f32 v0, v1, s0
	v_mul_f32_e32 v1, v22, v18
	ds_write_b16 v32, v0 offset:2496
	v_mul_f32_e32 v0, v6, v18
	v_fma_f32 v1, v86, v2, -v1
	v_fma_f32 v0, v70, v2, -v0
	v_mul_f32_e32 v4, v1, v1
	v_mul_f32_e32 v5, v38, v18
	v_fmac_f32_e32 v4, v0, v0
	v_fma_f32 v5, v102, v2, -v5
	v_mul_f32_e32 v6, v54, v18
	v_fmac_f32_e32 v4, v5, v5
	v_fma_f32 v2, v118, v2, -v6
	v_fmac_f32_e32 v4, v2, v2
	s_nop 1
	v_add_f32_dpp v4, v4, v4 quad_perm:[1,0,3,2] row_mask:0xf bank_mask:0xf
	s_nop 1
	v_add_f32_dpp v4, v4, v4 quad_perm:[2,3,0,1] row_mask:0xf bank_mask:0xf
	s_nop 1
	v_add_f32_dpp v4, v4, v4 row_half_mirror row_mask:0xf bank_mask:0xf
	s_nop 1
	v_add_f32_dpp v4, v4, v4 row_mirror row_mask:0xf bank_mask:0xf
	v_mov_b32_e32 v6, v4
	s_nop 1
	v_permlane16_swap_b32_e32 v4, v6
	v_add_f32_e32 v4, v4, v6
	v_fmamk_f32 v4, v4, 0x3c000000, v204
	v_rsq_f32_e32 v4, v4
	s_nop 0
	v_mul_f32_e32 v4, v133, v4
	v_mul_f32_e32 v0, v0, v4
	v_mul_f32_e32 v0, v132, v0
	v_mul_f32_e32 v1, v1, v4
	v_mul_f32_e32 v1, v131, v1
	v_mul_f32_e32 v5, v5, v4
	v_cvt_pk_bf16_f32 v0, v0, s0
	v_mul_f32_e32 v5, v130, v5
	v_mul_f32_e32 v2, v2, v4
	ds_write_b16 v32, v0 offset:2560
	v_cvt_pk_bf16_f32 v0, v1, s0
	v_mul_f32_e32 v2, v129, v2
	ds_write_b16 v32, v0 offset:2624
	v_cvt_pk_bf16_f32 v0, v5, s0
	ds_write_b16 v32, v0 offset:2688
	v_cvt_pk_bf16_f32 v0, v2, s0
	v_mul_f32_e32 v1, v23, v19
	ds_write_b16 v32, v0 offset:2752
	v_mul_f32_e32 v0, v7, v19
	v_fma_f32 v1, v87, v3, -v1
	v_fma_f32 v0, v71, v3, -v0
	v_mul_f32_e32 v2, v1, v1
	v_mul_f32_e32 v4, v39, v19
	v_fmac_f32_e32 v2, v0, v0
	v_fma_f32 v4, v103, v3, -v4
	v_mul_f32_e32 v5, v55, v19
	v_fmac_f32_e32 v2, v4, v4
	v_fma_f32 v3, v119, v3, -v5
	v_fmac_f32_e32 v2, v3, v3
	s_nop 1
	v_add_f32_dpp v2, v2, v2 quad_perm:[1,0,3,2] row_mask:0xf bank_mask:0xf
	s_nop 1
	v_add_f32_dpp v2, v2, v2 quad_perm:[2,3,0,1] row_mask:0xf bank_mask:0xf
	s_nop 1
	v_add_f32_dpp v2, v2, v2 row_half_mirror row_mask:0xf bank_mask:0xf
	s_nop 1
	v_add_f32_dpp v2, v2, v2 row_mirror row_mask:0xf bank_mask:0xf
	v_mov_b32_e32 v5, v2
	s_nop 1
	v_permlane16_swap_b32_e32 v2, v5
	v_add_f32_e32 v2, v2, v5
	v_fmamk_f32 v2, v2, 0x3c000000, v204
	v_rsq_f32_e32 v2, v2
	s_nop 0
	v_mul_f32_e32 v2, v133, v2
	v_mul_f32_e32 v0, v0, v2
	v_mul_f32_e32 v0, v132, v0
	v_mul_f32_e32 v1, v1, v2
	v_mul_f32_e32 v1, v131, v1
	v_mul_f32_e32 v4, v4, v2
	v_cvt_pk_bf16_f32 v0, v0, s0
	v_mul_f32_e32 v4, v130, v4
	v_mul_f32_e32 v2, v3, v2
	ds_write_b16 v32, v0 offset:2816
	v_cvt_pk_bf16_f32 v0, v1, s0
	v_mul_f32_e32 v2, v129, v2
	ds_write_b16 v32, v0 offset:2880
	v_cvt_pk_bf16_f32 v0, v4, s0
	ds_write_b16 v32, v0 offset:2944
	v_cvt_pk_bf16_f32 v0, v2, s0
	ds_write_b16 v32, v0 offset:3008
	ds_read_b128 v[0:3], v134 offset:64
	ds_read_b128 v[4:7], v134 offset:192
	s_waitcnt lgkmcnt(0)
	v_mul_f32_e32 v16, v24, v4
	v_mul_f32_e32 v8, v8, v4
	v_fma_f32 v16, v88, v0, -v16
	v_fma_f32 v8, v72, v0, -v8
	v_mul_f32_e32 v17, v16, v16
	v_mul_f32_e32 v18, v40, v4
	v_fmac_f32_e32 v17, v8, v8
	v_fma_f32 v18, v104, v0, -v18
	v_mul_f32_e32 v4, v56, v4
	v_fmac_f32_e32 v17, v18, v18
	v_fma_f32 v0, v120, v0, -v4
	v_fmac_f32_e32 v17, v0, v0
	s_nop 1
	v_add_f32_dpp v4, v17, v17 quad_perm:[1,0,3,2] row_mask:0xf bank_mask:0xf
	s_nop 1
	v_add_f32_dpp v4, v4, v4 quad_perm:[2,3,0,1] row_mask:0xf bank_mask:0xf
	s_nop 1
	v_add_f32_dpp v4, v4, v4 row_half_mirror row_mask:0xf bank_mask:0xf
	s_nop 1
	v_add_f32_dpp v4, v4, v4 row_mirror row_mask:0xf bank_mask:0xf
	v_mov_b32_e32 v17, v4
	s_nop 1
	v_permlane16_swap_b32_e32 v4, v17
	v_add_f32_e32 v4, v4, v17
	v_fmamk_f32 v4, v4, 0x3c000000, v204
	v_rsq_f32_e32 v4, v4
	s_nop 0
	v_mul_f32_e32 v4, v133, v4
	v_mul_f32_e32 v8, v8, v4
	v_mul_f32_e32 v8, v132, v8
	v_mul_f32_e32 v16, v16, v4
	v_mul_f32_e32 v16, v131, v16
	v_mul_f32_e32 v17, v18, v4
	v_mul_f32_e32 v0, v0, v4
	v_cvt_pk_bf16_f32 v4, v8, s0
	v_mul_f32_e32 v17, v130, v17
	ds_write_b16 v32, v4 offset:4096
	v_cvt_pk_bf16_f32 v4, v16, s0
	v_mul_f32_e32 v0, v129, v0
	ds_write_b16 v32, v4 offset:4160
	v_cvt_pk_bf16_f32 v4, v17, s0
	ds_write_b16 v32, v4 offset:4224
	v_cvt_pk_bf16_f32 v0, v0, s0
	v_mul_f32_e32 v4, v25, v5
	ds_write_b16 v32, v0 offset:4288
	v_mul_f32_e32 v0, v9, v5
	v_fma_f32 v4, v89, v1, -v4
	v_fma_f32 v0, v73, v1, -v0
	v_mul_f32_e32 v8, v4, v4
	v_mul_f32_e32 v9, v41, v5
	v_fmac_f32_e32 v8, v0, v0
	v_fma_f32 v9, v105, v1, -v9
	v_mul_f32_e32 v5, v57, v5
	v_fmac_f32_e32 v8, v9, v9
	v_fma_f32 v1, v121, v1, -v5
	v_fmac_f32_e32 v8, v1, v1
	s_nop 1
	v_add_f32_dpp v5, v8, v8 quad_perm:[1,0,3,2] row_mask:0xf bank_mask:0xf
	s_nop 1
	v_add_f32_dpp v5, v5, v5 quad_perm:[2,3,0,1] row_mask:0xf bank_mask:0xf
	s_nop 1
	v_add_f32_dpp v5, v5, v5 row_half_mirror row_mask:0xf bank_mask:0xf
	s_nop 1
	v_add_f32_dpp v5, v5, v5 row_mirror row_mask:0xf bank_mask:0xf
	v_mov_b32_e32 v8, v5
	s_nop 1
	v_permlane16_swap_b32_e32 v5, v8
	v_add_f32_e32 v5, v5, v8
	v_fmamk_f32 v5, v5, 0x3c000000, v204
	v_rsq_f32_e32 v5, v5
	s_nop 0
	v_mul_f32_e32 v5, v133, v5
	v_mul_f32_e32 v0, v0, v5
	v_mul_f32_e32 v0, v132, v0
	v_mul_f32_e32 v4, v4, v5
	v_mul_f32_e32 v4, v131, v4
	v_mul_f32_e32 v8, v9, v5
	v_cvt_pk_bf16_f32 v0, v0, s0
	v_mul_f32_e32 v8, v130, v8
	v_mul_f32_e32 v1, v1, v5
	ds_write_b16 v32, v0 offset:4352
	v_cvt_pk_bf16_f32 v0, v4, s0
	v_mul_f32_e32 v1, v129, v1
	ds_write_b16 v32, v0 offset:4416
	v_cvt_pk_bf16_f32 v0, v8, s0
	ds_write_b16 v32, v0 offset:4480
	v_cvt_pk_bf16_f32 v0, v1, s0
	v_mul_f32_e32 v1, v26, v6
	ds_write_b16 v32, v0 offset:4544
	v_mul_f32_e32 v0, v10, v6
	v_fma_f32 v1, v90, v2, -v1
	v_fma_f32 v0, v74, v2, -v0
	v_mul_f32_e32 v4, v1, v1
	v_mul_f32_e32 v5, v42, v6
	v_fmac_f32_e32 v4, v0, v0
	v_fma_f32 v5, v106, v2, -v5
	v_mul_f32_e32 v6, v58, v6
	v_fmac_f32_e32 v4, v5, v5
	v_fma_f32 v2, v122, v2, -v6
	v_fmac_f32_e32 v4, v2, v2
	s_nop 1
	v_add_f32_dpp v4, v4, v4 quad_perm:[1,0,3,2] row_mask:0xf bank_mask:0xf
	s_nop 1
	v_add_f32_dpp v4, v4, v4 quad_perm:[2,3,0,1] row_mask:0xf bank_mask:0xf
	s_nop 1
	v_add_f32_dpp v4, v4, v4 row_half_mirror row_mask:0xf bank_mask:0xf
	s_nop 1
	v_add_f32_dpp v4, v4, v4 row_mirror row_mask:0xf bank_mask:0xf
	v_mov_b32_e32 v6, v4
	s_nop 1
	v_permlane16_swap_b32_e32 v4, v6
	v_add_f32_e32 v4, v4, v6
	v_fmamk_f32 v4, v4, 0x3c000000, v204
	v_rsq_f32_e32 v4, v4
	s_nop 0
	v_mul_f32_e32 v4, v133, v4
	v_mul_f32_e32 v0, v0, v4
	v_mul_f32_e32 v0, v132, v0
	v_mul_f32_e32 v1, v1, v4
	v_mul_f32_e32 v1, v131, v1
	v_mul_f32_e32 v5, v5, v4
	v_cvt_pk_bf16_f32 v0, v0, s0
	v_mul_f32_e32 v5, v130, v5
	v_mul_f32_e32 v2, v2, v4
	ds_write_b16 v32, v0 offset:4608
	v_cvt_pk_bf16_f32 v0, v1, s0
	v_mul_f32_e32 v2, v129, v2
	ds_write_b16 v32, v0 offset:4672
	v_cvt_pk_bf16_f32 v0, v5, s0
	ds_write_b16 v32, v0 offset:4736
	v_cvt_pk_bf16_f32 v0, v2, s0
	v_mul_f32_e32 v1, v27, v7
	ds_write_b16 v32, v0 offset:4800
	v_mul_f32_e32 v0, v11, v7
	v_fma_f32 v1, v91, v3, -v1
	v_fma_f32 v0, v75, v3, -v0
	v_mul_f32_e32 v2, v1, v1
	v_mul_f32_e32 v4, v43, v7
	v_fmac_f32_e32 v2, v0, v0
	v_fma_f32 v4, v107, v3, -v4
	v_mul_f32_e32 v5, v59, v7
	v_fmac_f32_e32 v2, v4, v4
	v_fma_f32 v3, v123, v3, -v5
	v_fmac_f32_e32 v2, v3, v3
	s_nop 1
	v_add_f32_dpp v2, v2, v2 quad_perm:[1,0,3,2] row_mask:0xf bank_mask:0xf
	s_nop 1
	v_add_f32_dpp v2, v2, v2 quad_perm:[2,3,0,1] row_mask:0xf bank_mask:0xf
	s_nop 1
	v_add_f32_dpp v2, v2, v2 row_half_mirror row_mask:0xf bank_mask:0xf
	s_nop 1
	v_add_f32_dpp v2, v2, v2 row_mirror row_mask:0xf bank_mask:0xf
	v_mov_b32_e32 v5, v2
	s_nop 1
	v_permlane16_swap_b32_e32 v2, v5
	v_add_f32_e32 v2, v2, v5
	v_fmamk_f32 v2, v2, 0x3c000000, v204
	v_rsq_f32_e32 v2, v2
	s_nop 0
	v_mul_f32_e32 v2, v133, v2
	v_mul_f32_e32 v0, v0, v2
	v_mul_f32_e32 v0, v132, v0
	v_mul_f32_e32 v1, v1, v2
	v_mul_f32_e32 v1, v131, v1
	v_mul_f32_e32 v4, v4, v2
	v_cvt_pk_bf16_f32 v0, v0, s0
	v_mul_f32_e32 v4, v130, v4
	v_mul_f32_e32 v2, v3, v2
	ds_write_b16 v32, v0 offset:4864
	v_cvt_pk_bf16_f32 v0, v1, s0
	v_mul_f32_e32 v2, v129, v2
	ds_write_b16 v32, v0 offset:4928
	v_cvt_pk_bf16_f32 v0, v4, s0
	ds_write_b16 v32, v0 offset:4992
	v_cvt_pk_bf16_f32 v0, v2, s0
	ds_write_b16 v32, v0 offset:5056
	ds_read_b128 v[0:3], v134 offset:96
	ds_read_b128 v[4:7], v134 offset:224
	s_waitcnt lgkmcnt(0)
	v_mul_f32_e32 v9, v28, v4
	v_mul_f32_e32 v8, v12, v4
	v_fma_f32 v9, v92, v0, -v9
	v_fma_f32 v8, v76, v0, -v8
	v_mul_f32_e32 v10, v9, v9
	v_mul_f32_e32 v11, v44, v4
	v_fmac_f32_e32 v10, v8, v8
	v_fma_f32 v11, v108, v0, -v11
	v_mul_f32_e32 v4, v60, v4
	v_fmac_f32_e32 v10, v11, v11
	v_fma_f32 v0, v124, v0, -v4
	v_fmac_f32_e32 v10, v0, v0
	s_nop 1
	v_add_f32_dpp v4, v10, v10 quad_perm:[1,0,3,2] row_mask:0xf bank_mask:0xf
	s_nop 1
	v_add_f32_dpp v4, v4, v4 quad_perm:[2,3,0,1] row_mask:0xf bank_mask:0xf
	s_nop 1
	v_add_f32_dpp v4, v4, v4 row_half_mirror row_mask:0xf bank_mask:0xf
	s_nop 1
	v_add_f32_dpp v4, v4, v4 row_mirror row_mask:0xf bank_mask:0xf
	v_mov_b32_e32 v10, v4
	s_nop 1
	v_permlane16_swap_b32_e32 v4, v10
	v_add_f32_e32 v4, v4, v10
	v_fmamk_f32 v4, v4, 0x3c000000, v204
	v_rsq_f32_e32 v4, v4
	s_nop 0
	v_mul_f32_e32 v4, v133, v4
	v_mul_f32_e32 v8, v8, v4
	v_mul_f32_e32 v8, v132, v8
	v_mul_f32_e32 v9, v9, v4
	v_mul_f32_e32 v9, v131, v9
	v_mul_f32_e32 v10, v11, v4
	v_mul_f32_e32 v0, v0, v4
	v_cvt_pk_bf16_f32 v4, v8, s0
	v_mul_f32_e32 v10, v130, v10
	ds_write_b16 v32, v4 offset:6144
	v_cvt_pk_bf16_f32 v4, v9, s0
	v_mul_f32_e32 v0, v129, v0
	ds_write_b16 v32, v4 offset:6208
	v_cvt_pk_bf16_f32 v4, v10, s0
	ds_write_b16 v32, v4 offset:6272
	v_cvt_pk_bf16_f32 v0, v0, s0
	v_mul_f32_e32 v4, v29, v5
	ds_write_b16 v32, v0 offset:6336
	v_mul_f32_e32 v0, v13, v5
	v_fma_f32 v4, v93, v1, -v4
	v_fma_f32 v0, v77, v1, -v0
	v_mul_f32_e32 v8, v4, v4
	v_mul_f32_e32 v9, v45, v5
	v_fmac_f32_e32 v8, v0, v0
	v_fma_f32 v9, v109, v1, -v9
	v_mul_f32_e32 v5, v61, v5
	v_fmac_f32_e32 v8, v9, v9
	v_fma_f32 v1, v125, v1, -v5
	v_fmac_f32_e32 v8, v1, v1
	s_nop 1
	v_add_f32_dpp v5, v8, v8 quad_perm:[1,0,3,2] row_mask:0xf bank_mask:0xf
	s_nop 1
	v_add_f32_dpp v5, v5, v5 quad_perm:[2,3,0,1] row_mask:0xf bank_mask:0xf
	s_nop 1
	v_add_f32_dpp v5, v5, v5 row_half_mirror row_mask:0xf bank_mask:0xf
	s_nop 1
	v_add_f32_dpp v5, v5, v5 row_mirror row_mask:0xf bank_mask:0xf
	v_mov_b32_e32 v8, v5
	s_nop 1
	v_permlane16_swap_b32_e32 v5, v8
	v_add_f32_e32 v5, v5, v8
	v_fmamk_f32 v5, v5, 0x3c000000, v204
	v_rsq_f32_e32 v5, v5
	s_nop 0
	v_mul_f32_e32 v5, v133, v5
	v_mul_f32_e32 v0, v0, v5
	v_mul_f32_e32 v0, v132, v0
	v_mul_f32_e32 v4, v4, v5
	v_mul_f32_e32 v4, v131, v4
	v_mul_f32_e32 v8, v9, v5
	v_cvt_pk_bf16_f32 v0, v0, s0
	v_mul_f32_e32 v8, v130, v8
	v_mul_f32_e32 v1, v1, v5
	ds_write_b16 v32, v0 offset:6400
	v_cvt_pk_bf16_f32 v0, v4, s0
	v_mul_f32_e32 v1, v129, v1
	ds_write_b16 v32, v0 offset:6464
	v_cvt_pk_bf16_f32 v0, v8, s0
	ds_write_b16 v32, v0 offset:6528
	v_cvt_pk_bf16_f32 v0, v1, s0
	v_mul_f32_e32 v1, v30, v6
	ds_write_b16 v32, v0 offset:6592
	v_mul_f32_e32 v0, v14, v6
	v_fma_f32 v1, v94, v2, -v1
	v_fma_f32 v0, v78, v2, -v0
	v_mul_f32_e32 v4, v1, v1
	v_mul_f32_e32 v5, v46, v6
	v_fmac_f32_e32 v4, v0, v0
	v_fma_f32 v5, v110, v2, -v5
	v_mul_f32_e32 v6, v62, v6
	v_fmac_f32_e32 v4, v5, v5
	v_fma_f32 v2, v126, v2, -v6
	v_fmac_f32_e32 v4, v2, v2
	s_nop 1
	v_add_f32_dpp v4, v4, v4 quad_perm:[1,0,3,2] row_mask:0xf bank_mask:0xf
	s_nop 1
	v_add_f32_dpp v4, v4, v4 quad_perm:[2,3,0,1] row_mask:0xf bank_mask:0xf
	s_nop 1
	v_add_f32_dpp v4, v4, v4 row_half_mirror row_mask:0xf bank_mask:0xf
	s_nop 1
	v_add_f32_dpp v4, v4, v4 row_mirror row_mask:0xf bank_mask:0xf
	v_mov_b32_e32 v6, v4
	s_nop 1
	v_permlane16_swap_b32_e32 v4, v6
	v_add_f32_e32 v4, v4, v6
	v_fmamk_f32 v4, v4, 0x3c000000, v204
	v_rsq_f32_e32 v4, v4
	s_nop 0
	v_mul_f32_e32 v4, v133, v4
	v_mul_f32_e32 v0, v0, v4
	v_mul_f32_e32 v0, v132, v0
	v_mul_f32_e32 v1, v1, v4
	v_mul_f32_e32 v1, v131, v1
	v_mul_f32_e32 v5, v5, v4
	v_cvt_pk_bf16_f32 v0, v0, s0
	v_mul_f32_e32 v5, v130, v5
	v_mul_f32_e32 v2, v2, v4
	ds_write_b16 v32, v0 offset:6656
	v_cvt_pk_bf16_f32 v0, v1, s0
	v_mul_f32_e32 v2, v129, v2
	ds_write_b16 v32, v0 offset:6720
	v_cvt_pk_bf16_f32 v0, v5, s0
	ds_write_b16 v32, v0 offset:6784
	v_cvt_pk_bf16_f32 v0, v2, s0
	v_mul_f32_e32 v1, v31, v7
	ds_write_b16 v32, v0 offset:6848
	v_mul_f32_e32 v0, v15, v7
	v_fma_f32 v1, v95, v3, -v1
	v_fma_f32 v0, v79, v3, -v0
	v_mul_f32_e32 v2, v1, v1
	v_mul_f32_e32 v4, v47, v7
	v_fmac_f32_e32 v2, v0, v0
	v_fma_f32 v4, v111, v3, -v4
	v_mul_f32_e32 v5, v63, v7
	v_fmac_f32_e32 v2, v4, v4
	v_fma_f32 v3, v127, v3, -v5
	v_fmac_f32_e32 v2, v3, v3
	s_nop 1
	v_add_f32_dpp v2, v2, v2 quad_perm:[1,0,3,2] row_mask:0xf bank_mask:0xf
	s_nop 1
	v_add_f32_dpp v2, v2, v2 quad_perm:[2,3,0,1] row_mask:0xf bank_mask:0xf
	s_nop 1
	v_add_f32_dpp v2, v2, v2 row_half_mirror row_mask:0xf bank_mask:0xf
	s_nop 1
	v_add_f32_dpp v2, v2, v2 row_mirror row_mask:0xf bank_mask:0xf
	v_mov_b32_e32 v5, v2
	s_nop 1
	v_permlane16_swap_b32_e32 v2, v5
	v_add_f32_e32 v2, v2, v5
	v_fmamk_f32 v2, v2, 0x3c000000, v204
	v_rsq_f32_e32 v2, v2
	s_nop 0
	v_mul_f32_e32 v2, v133, v2
	v_mul_f32_e32 v0, v0, v2
	v_mul_f32_e32 v0, v132, v0
	v_mul_f32_e32 v1, v1, v2
	v_mul_f32_e32 v1, v131, v1
	v_mul_f32_e32 v4, v4, v2
	v_cvt_pk_bf16_f32 v0, v0, s0
	v_mul_f32_e32 v4, v130, v4
	v_mul_f32_e32 v2, v3, v2
	ds_write_b16 v32, v0 offset:6912
	v_cvt_pk_bf16_f32 v0, v1, s0
	v_mul_f32_e32 v2, v129, v2
	ds_write_b16 v32, v0 offset:6976
	v_cvt_pk_bf16_f32 v0, v4, s0
	ds_write_b16 v32, v0 offset:7040
	v_cvt_pk_bf16_f32 v0, v2, s0
	ds_write_b16 v32, v0 offset:7104
	v_lshlrev_b32_e32 v0, 4, v128
	v_and_b32_e32 v160, 0xf0, v0
	v_add_u32_e32 v6, s48, v160
	v_ashrrev_i32_e32 v4, 4, v128
	s_waitcnt lgkmcnt(0)
	v_mov_b32_e32 v40, v4
	v_lshl_add_u32 v48, v40, 8, v6
	ds_read_b128 v[8:11], v48
	v_add_u32_e32 v48, 0x40, v128
	v_ashrrev_i32_e32 v41, 4, v48
	v_lshl_add_u32 v48, v41, 8, v6
	ds_read_b128 v[12:15], v48
	v_add_u32_e32 v48, 0x80, v128
	v_ashrrev_i32_e32 v42, 4, v48
	v_lshl_add_u32 v48, v42, 8, v6
	ds_read_b128 v[16:19], v48
	v_add_u32_e32 v48, 0xc0, v128
	v_ashrrev_i32_e32 v43, 4, v48
	v_lshl_add_u32 v48, v43, 8, v6
	ds_read_b128 v[20:23], v48
	v_add_u32_e32 v48, 0x100, v128
	v_ashrrev_i32_e32 v44, 4, v48
	v_lshl_add_u32 v48, v44, 8, v6
	ds_read_b128 v[24:27], v48
	v_add_u32_e32 v48, 0x140, v128
	v_ashrrev_i32_e32 v45, 4, v48
	v_lshl_add_u32 v48, v45, 8, v6
	ds_read_b128 v[28:31], v48
	v_add_u32_e32 v48, 0x180, v128
	v_ashrrev_i32_e32 v46, 4, v48
	v_lshl_add_u32 v48, v46, 8, v6
	ds_read_b128 v[32:35], v48
	v_add_u32_e32 v48, 0x1c0, v128
	v_ashrrev_i32_e32 v47, 4, v48
	v_lshl_add_u32 v48, v47, 8, v6
	ds_read_b128 v[36:39], v48
	v_mov_b32_e32 v4, v40
	v_ashrrev_i32_e32 v5, 31, v4
	v_lshl_add_u64 v[4:5], s[2:3], 0, v[4:5]
	v_lshlrev_b64 v[4:5], 11, v[4:5]
	v_lshl_add_u64 v[4:5], s[92:93], 0, v[4:5]
	v_lshl_add_u64 v[4:5], v[4:5], 0, v[160:161]
	s_waitcnt lgkmcnt(7)
	global_store_dwordx4 v[4:5], v[8:11], off
	v_mov_b32_e32 v4, v41
	v_ashrrev_i32_e32 v5, 31, v4
	v_lshl_add_u64 v[4:5], s[2:3], 0, v[4:5]
	v_lshlrev_b64 v[4:5], 11, v[4:5]
	v_lshl_add_u64 v[4:5], s[92:93], 0, v[4:5]
	v_lshl_add_u64 v[4:5], v[4:5], 0, v[160:161]
	s_waitcnt lgkmcnt(6)
	global_store_dwordx4 v[4:5], v[12:15], off
	v_mov_b32_e32 v4, v42
	v_ashrrev_i32_e32 v5, 31, v4
	v_lshl_add_u64 v[4:5], s[2:3], 0, v[4:5]
	v_lshlrev_b64 v[4:5], 11, v[4:5]
	v_lshl_add_u64 v[4:5], s[92:93], 0, v[4:5]
	v_lshl_add_u64 v[4:5], v[4:5], 0, v[160:161]
	s_waitcnt lgkmcnt(5)
	global_store_dwordx4 v[4:5], v[16:19], off
	v_mov_b32_e32 v4, v43
	v_ashrrev_i32_e32 v5, 31, v4
	v_lshl_add_u64 v[4:5], s[2:3], 0, v[4:5]
	v_lshlrev_b64 v[4:5], 11, v[4:5]
	v_lshl_add_u64 v[4:5], s[92:93], 0, v[4:5]
	v_lshl_add_u64 v[4:5], v[4:5], 0, v[160:161]
	s_waitcnt lgkmcnt(4)
	global_store_dwordx4 v[4:5], v[20:23], off
	v_mov_b32_e32 v4, v44
	v_ashrrev_i32_e32 v5, 31, v4
	v_lshl_add_u64 v[4:5], s[2:3], 0, v[4:5]
	v_lshlrev_b64 v[4:5], 11, v[4:5]
	v_lshl_add_u64 v[4:5], s[92:93], 0, v[4:5]
	v_lshl_add_u64 v[4:5], v[4:5], 0, v[160:161]
	s_waitcnt lgkmcnt(3)
	global_store_dwordx4 v[4:5], v[24:27], off
	v_mov_b32_e32 v4, v45
	v_ashrrev_i32_e32 v5, 31, v4
	v_lshl_add_u64 v[4:5], s[2:3], 0, v[4:5]
	v_lshlrev_b64 v[4:5], 11, v[4:5]
	v_lshl_add_u64 v[4:5], s[92:93], 0, v[4:5]
	v_lshl_add_u64 v[4:5], v[4:5], 0, v[160:161]
	s_waitcnt lgkmcnt(2)
	global_store_dwordx4 v[4:5], v[28:31], off
	v_mov_b32_e32 v4, v46
	v_ashrrev_i32_e32 v5, 31, v4
	v_lshl_add_u64 v[4:5], s[2:3], 0, v[4:5]
	v_lshlrev_b64 v[4:5], 11, v[4:5]
	v_lshl_add_u64 v[4:5], s[92:93], 0, v[4:5]
	v_lshl_add_u64 v[4:5], v[4:5], 0, v[160:161]
	s_waitcnt lgkmcnt(1)
	global_store_dwordx4 v[4:5], v[32:35], off
	v_mov_b32_e32 v4, v47
	v_ashrrev_i32_e32 v5, 31, v4
	v_lshl_add_u64 v[4:5], s[2:3], 0, v[4:5]
	v_lshlrev_b64 v[4:5], 11, v[4:5]
	v_lshl_add_u64 v[4:5], s[92:93], 0, v[4:5]
	v_lshl_add_u64 v[4:5], v[4:5], 0, v[160:161]
	s_waitcnt lgkmcnt(0)
	global_store_dwordx4 v[4:5], v[36:39], off
	s_waitcnt lgkmcnt(0)
	s_barrier
	s_cbranch_scc1 .LBB0_419
.LBB0_406:
	s_lshl_b32 s2, s6, 4
	v_readlane_b32 s3, v254, 17
	s_add_i32 s2, s3, s2
	s_ashr_i32 s4, s2, 3
	v_mbcnt_lo_u32_b32 v9, -1, 0
	v_mbcnt_hi_u32_b32 v9, -1, v9
	s_ashr_i32 s5, s4, 31
	v_ashrrev_i32_e32 v0, 3, v9
	v_add_u32_e32 v1, s36, v0
	s_lshl_b64 s[2:3], s[4:5], 12
	v_lshrrev_b32_e32 v1, 1, v1
	v_xor_b32_e32 v1, v1, v9
	s_add_i32 s5, s2, s36
	v_lshlrev_b32_e32 v1, 3, v1
	v_add_lshl_u32 v11, s5, v0, 10
	v_readlane_b32 s5, v254, 4
	v_and_b32_e32 v10, 56, v1
	v_ashrrev_i32_e32 v1, 4, v9
	s_add_i32 s5, s5, s2
	v_add_lshl_u32 v13, s5, v1, 10
	v_readlane_b32 s5, v254, 6
	v_and_b32_e32 v2, 15, v9
	v_lshlrev_b32_e32 v3, 2, v1
	s_add_u32 s2, s2, s5
	v_readlane_b32 s5, v254, 7
	v_lshrrev_b32_e32 v1, 4, v9
	v_bitop3_b32 v2, v3, v2, 12 bitop3:0x6c
	s_addc_u32 s3, s3, s5
	v_xor_b32_e32 v4, v1, v9
	v_ashrrev_i32_e32 v1, 31, v0
	v_lshlrev_b32_e32 v12, 3, v2
	v_lshl_add_u64 v[2:3], s[2:3], 0, v[0:1]
	v_lshlrev_b32_e32 v1, 4, v4
	v_and_b32_e32 v160, 0x70, v1
	v_add_u32_e32 v1, 64, v9
	v_ashrrev_i32_e32 v4, 3, v1
	v_lshrrev_b32_e32 v1, 4, v1
	v_ashrrev_i32_e32 v5, 31, v4
	v_xor_b32_e32 v1, v1, v9
	v_lshl_add_u64 v[4:5], s[2:3], 0, v[4:5]
	v_lshlrev_b64 v[4:5], 11, v[4:5]
	v_lshlrev_b32_e32 v1, 4, v1
	v_lshl_add_u64 v[4:5], s[92:93], 0, v[4:5]
	v_and_b32_e32 v6, 0x70, v1
	v_mov_b32_e32 v7, v161
	v_add_u32_e32 v1, 0x80, v9
	v_lshl_add_u64 v[4:5], v[4:5], 0, v[6:7]
	v_ashrrev_i32_e32 v6, 3, v1
	v_add_u32_e32 v1, 0xc0, v9
	v_lshlrev_b64 v[2:3], 11, v[2:3]
	v_readlane_b32 s5, v254, 5
	v_ashrrev_i32_e32 v7, 31, v6
	v_ashrrev_i32_e32 v8, 3, v1
	v_lshrrev_b32_e32 v1, 4, v1
	v_lshl_add_u64 v[2:3], s[92:93], 0, v[2:3]
	s_add_i32 s5, s5, 0
	v_lshl_add_u64 v[6:7], s[2:3], 0, v[6:7]
	v_xor_b32_e32 v1, v1, v9
	v_ashrrev_i32_e32 v9, 31, v8
	v_lshl_add_u64 v[2:3], v[2:3], 0, v[160:161]
	s_add_i32 s7, s5, 0x10000
	s_mov_b32 s8, m0
	s_mov_b32 m0, s7
	s_nop 0
	global_load_lds_dwordx4 v[2:3], off
	s_mov_b32 m0, s8
	v_lshlrev_b64 v[6:7], 11, v[6:7]
	v_lshl_add_u64 v[8:9], s[2:3], 0, v[8:9]
	s_add_i32 s7, s5, 0x10400
	s_mov_b32 s8, m0
	s_mov_b32 m0, s7
	s_nop 0
	global_load_lds_dwordx4 v[4:5], off
	s_mov_b32 m0, s8
	v_lshl_add_u64 v[6:7], s[92:93], 0, v[6:7]
	v_lshlrev_b64 v[8:9], 11, v[8:9]
	v_lshlrev_b32_e32 v1, 4, v1
	v_lshl_add_u64 v[6:7], v[6:7], 0, v[160:161]
	s_add_i32 s7, s5, 0x10800
	s_mov_b32 s8, m0
	s_mov_b32 m0, s7
	s_nop 0
	global_load_lds_dwordx4 v[6:7], off
	s_mov_b32 m0, s8
	v_lshl_add_u64 v[8:9], s[92:93], 0, v[8:9]
	v_and_b32_e32 v160, 0x70, v1
	v_lshl_add_u64 v[8:9], v[8:9], 0, v[160:161]
	s_add_i32 s7, s5, 0x10c00
	s_mov_b32 s8, m0
	s_mov_b32 m0, s7
	s_nop 0
	global_load_lds_dwordx4 v[8:9], off
	s_mov_b32 m0, s8
	v_lshl_add_u64 v[2:3], v[2:3], 0, s[38:39]
	s_add_i32 s7, s5, 0x11000
	s_mov_b32 s8, m0
	s_mov_b32 m0, s7
	s_nop 0
	global_load_lds_dwordx4 v[2:3], off
	s_mov_b32 m0, s8
	v_lshl_add_u64 v[2:3], v[4:5], 0, s[38:39]
	s_add_i32 s7, s5, 0x11400
	s_mov_b32 s8, m0
	s_mov_b32 m0, s7
	s_nop 0
	global_load_lds_dwordx4 v[2:3], off
	s_mov_b32 m0, s8
	v_lshl_add_u64 v[2:3], v[6:7], 0, s[38:39]
	s_add_i32 s7, s5, 0x11800
	s_mov_b32 s8, m0
	s_mov_b32 m0, s7
	s_nop 0
	global_load_lds_dwordx4 v[2:3], off
	s_mov_b32 m0, s8
	v_lshl_add_u64 v[2:3], v[8:9], 0, s[38:39]
	s_add_i32 s5, s5, 0x11c00
	s_mov_b32 s7, m0
	s_mov_b32 m0, s5
	s_nop 0
	global_load_lds_dwordx4 v[2:3], off
	s_mov_b32 m0, s7
	v_or3_b32 v160, v10, v11, s40
	v_lshl_add_u64 v[4:5], v[160:161], 1, s[66:67]
	s_mov_b32 s5, m0
	s_mov_b32 m0, s49
	s_nop 0
	global_load_lds_dwordx4 v[4:5], off
	s_mov_b32 m0, s5
	v_or3_b32 v2, v12, v13, s40
	v_lshl_add_u64 v[4:5], v[4:5], 0, s[38:39]
	s_mov_b32 s5, m0
	s_mov_b32 m0, s33
	s_nop 0
	global_load_lds_dwordx4 v[4:5], off
	s_mov_b32 m0, s5
	v_mov_b32_e32 v3, v161
	v_lshl_add_u64 v[4:5], v[2:3], 1, s[68:69]
	s_mov_b32 s5, m0
	s_mov_b32 m0, s54
	s_nop 0
	global_load_lds_dwordx4 v[4:5], off
	s_mov_b32 m0, s5
	v_add_u32_e32 v160, 0x8000, v2
	v_lshl_add_u64 v[2:3], v[160:161], 1, s[68:69]
	s_mov_b32 s5, m0
	s_mov_b32 m0, s47
	s_nop 0
	global_load_lds_dwordx4 v[2:3], off
	s_mov_b32 m0, s5
	s_lshl_b32 s4, s4, 22
	v_readlane_b32 s5, v255, 1
	s_add_i32 s4, s5, s4
	v_lshlrev_b32_e32 v0, 10, v0
	v_or_b32_e32 v1, s40, v13
	v_add3_u32 v202, s4, v0, v10
	v_mov_b32_e32 v0, 0
	v_add_u32_e32 v201, v1, v12
	s_mov_b32 s4, 0
	s_mov_b32 s5, 0
	v_mov_b32_e32 v1, v0
	v_mov_b32_e32 v2, v0
	v_mov_b32_e32 v3, v0
	v_mov_b32_e32 v4, v0
	v_mov_b32_e32 v5, v0
	v_mov_b32_e32 v6, v0
	v_mov_b32_e32 v7, v0
	v_mov_b32_e32 v8, v0
	v_mov_b32_e32 v9, v0
	v_mov_b32_e32 v10, v0
	v_mov_b32_e32 v11, v0
	v_mov_b32_e32 v12, v0
	v_mov_b32_e32 v13, v0
	v_mov_b32_e32 v14, v0
	v_mov_b32_e32 v15, v0
	v_mov_b32_e32 v16, v0
	v_mov_b32_e32 v17, v0
	v_mov_b32_e32 v18, v0
	v_mov_b32_e32 v19, v0
	v_mov_b32_e32 v20, v0
	v_mov_b32_e32 v21, v0
	v_mov_b32_e32 v22, v0
	v_mov_b32_e32 v23, v0
	v_mov_b32_e32 v24, v0
	v_mov_b32_e32 v25, v0
	v_mov_b32_e32 v26, v0
	v_mov_b32_e32 v27, v0
	v_mov_b32_e32 v28, v0
	v_mov_b32_e32 v29, v0
	v_mov_b32_e32 v30, v0
	v_mov_b32_e32 v31, v0
	v_mov_b32_e32 v32, v0
	v_mov_b32_e32 v33, v0
	v_mov_b32_e32 v34, v0
	v_mov_b32_e32 v35, v0
	v_mov_b32_e32 v36, v0
	v_mov_b32_e32 v37, v0
	v_mov_b32_e32 v38, v0
	v_mov_b32_e32 v39, v0
	v_mov_b32_e32 v40, v0
	v_mov_b32_e32 v41, v0
	v_mov_b32_e32 v42, v0
	v_mov_b32_e32 v43, v0
	v_mov_b32_e32 v44, v0
	v_mov_b32_e32 v45, v0
	v_mov_b32_e32 v46, v0
	v_mov_b32_e32 v47, v0
	v_mov_b32_e32 v48, v0
	v_mov_b32_e32 v49, v0
	v_mov_b32_e32 v50, v0
	v_mov_b32_e32 v51, v0
	v_mov_b32_e32 v52, v0
	v_mov_b32_e32 v53, v0
	v_mov_b32_e32 v54, v0
	v_mov_b32_e32 v55, v0
	v_mov_b32_e32 v56, v0
	v_mov_b32_e32 v57, v0
	v_mov_b32_e32 v58, v0
	v_mov_b32_e32 v59, v0
	v_mov_b32_e32 v60, v0
	v_mov_b32_e32 v61, v0
	v_mov_b32_e32 v62, v0
	v_mov_b32_e32 v63, v0
	v_mov_b32_e32 v64, v0
	v_mov_b32_e32 v65, v0
	v_mov_b32_e32 v66, v0
	v_mov_b32_e32 v67, v0
	v_mov_b32_e32 v68, v0
	v_mov_b32_e32 v69, v0
	v_mov_b32_e32 v70, v0
	v_mov_b32_e32 v71, v0
	v_mov_b32_e32 v72, v0
	v_mov_b32_e32 v73, v0
	v_mov_b32_e32 v74, v0
	v_mov_b32_e32 v75, v0
	v_mov_b32_e32 v76, v0
	v_mov_b32_e32 v77, v0
	v_mov_b32_e32 v78, v0
	v_mov_b32_e32 v79, v0
	v_mov_b32_e32 v80, v0
	v_mov_b32_e32 v81, v0
	v_mov_b32_e32 v82, v0
	v_mov_b32_e32 v83, v0
	v_mov_b32_e32 v84, v0
	v_mov_b32_e32 v85, v0
	v_mov_b32_e32 v86, v0
	v_mov_b32_e32 v87, v0
	v_mov_b32_e32 v88, v0
	v_mov_b32_e32 v89, v0
	v_mov_b32_e32 v90, v0
	v_mov_b32_e32 v91, v0
	v_mov_b32_e32 v92, v0
	v_mov_b32_e32 v93, v0
	v_mov_b32_e32 v94, v0
	v_mov_b32_e32 v95, v0
	v_mov_b32_e32 v96, v0
	v_mov_b32_e32 v97, v0
	v_mov_b32_e32 v98, v0
	v_mov_b32_e32 v99, v0
	v_mov_b32_e32 v100, v0
	v_mov_b32_e32 v101, v0
	v_mov_b32_e32 v102, v0
	v_mov_b32_e32 v103, v0
	v_mov_b32_e32 v104, v0
	v_mov_b32_e32 v105, v0
	v_mov_b32_e32 v106, v0
	v_mov_b32_e32 v107, v0
	v_mov_b32_e32 v108, v0
	v_mov_b32_e32 v109, v0
	v_mov_b32_e32 v110, v0
	v_mov_b32_e32 v111, v0
	v_mov_b32_e32 v112, v0
	v_mov_b32_e32 v113, v0
	v_mov_b32_e32 v114, v0
	v_mov_b32_e32 v115, v0
	v_mov_b32_e32 v116, v0
	v_mov_b32_e32 v117, v0
	v_mov_b32_e32 v118, v0
	v_mov_b32_e32 v119, v0
	v_mov_b32_e32 v120, v0
	v_mov_b32_e32 v121, v0
	v_mov_b32_e32 v122, v0
	v_mov_b32_e32 v123, v0
	v_mov_b32_e32 v124, v0
	v_mov_b32_e32 v125, v0
	v_mov_b32_e32 v126, v0
	v_mov_b32_e32 v127, v0
	v_mov_b32_e32 v166, v0
	v_mov_b32_e32 v167, v0
	s_waitcnt vmcnt(0)
	v_readlane_b32 s98, v253, 39
	s_cmpk_ge_u32 s98, 0x100
	s_cbranch_scc0 .Lattn_prio_skip_a
	s_setprio 1
